# idle-slot deferral: both FFN weight transposes (W7 with gain, W8) of layers 1-3 moved from the prologue into the idle half of the previous layer's FFN-up 9th round
# speedup vs baseline: 1.0160x; 1.0035x over previous
.LBB0_35:
	s_or_b64 exec, exec, s[4:5]
	s_lshl_b32 s4, s14, 14
	s_add_i32 s4, s4, 0
	s_add_u32 s19, s16, 0x76b32000
	s_addc_u32 s23, s17, 0
	s_add_u32 s25, s16, 0x6eb32000
	s_addc_u32 s40, s17, 0
	s_add_u32 s41, s16, 0x6ab32000
	s_addc_u32 s42, s17, 0
	s_add_u32 s43, s16, 0x6bb32000
	s_addc_u32 s44, s17, 0
	s_add_u32 s13, s16, 0x69332000
	s_addc_u32 s15, s17, 0
	s_add_u32 s45, s16, 0x68732000
	s_addc_u32 s47, s17, 0
	s_add_u32 s48, s16, 0x68132000
	s_addc_u32 s49, s17, 0
	s_add_u32 s50, s16, 0x67732000
	s_addc_u32 s51, s17, 0
	v_lshrrev_b32_e32 v40, 3, v1
	s_add_u32 s52, s16, 0x69b32000
	v_mul_u32_u24_e32 v5, 0x420, v10
	v_lshlrev_b32_e32 v6, 2, v40
	s_addc_u32 s53, s17, 0
	v_lshl_add_u32 v3, v10, 4, s4
	v_add3_u32 v51, s4, v5, v6
	s_lshl_b32 s54, s46, 10
	s_lshl_b32 s4, s14, 7
	s_add_i32 s54, s54, s4
	s_lshl_b32 s4, s14, 6
	v_lshlrev_b32_e32 v34, 2, v1
	s_add_i32 s56, s56, s4
	s_lshl_b32 s4, s46, 8
	s_lshl_b32 s5, s14, 5
	v_and_b32_e32 v2, 28, v34
	v_mov_b32_e32 v43, 0
	v_mul_u32_u24_e32 v4, 0x84, v40
	v_or_b32_e32 v35, 8, v40
	v_or_b32_e32 v49, 16, v40
	v_or_b32_e32 v50, 24, v40
	v_lshlrev_b32_e32 v52, 1, v40
	v_mov_b32_e32 v5, 0x800
	s_add_i32 s57, s4, s5
	s_mov_b32 s7, 0
	v_or_b32_e32 v53, 0x800, v52
	v_lshl_or_b32 v54, v35, 1, v5
	v_lshl_or_b32 v55, v49, 1, v5
	v_lshl_or_b32 v56, v50, 1, v5
	v_mov_b32_e32 v41, v43
	s_lshl_b32 s55, s58, 10
	s_addk_i32 s57, 0xfe00
	s_lshl_b32 s58, s58, 8
	v_lshlrev_b32_e32 v42, 2, v2
	s_movk_i32 s59, 0x1000
	s_movk_i32 s60, 0x7ff
	s_mov_b32 s61, 0x2aaaaaab
	s_movk_i32 s62, 0xc0
	s_movk_i32 s63, 0x7f
	s_movk_i32 s64, 0xff40
	s_movk_i32 s65, 0x1ff
	v_add_u32_e32 v57, v3, v4
	s_mov_b32 s66, 6
	s_branch .LBB0_37

.LBB0_1964:
	s_waitcnt vmcnt(0)
	v_readlane_b32 s86, v255, 26
	v_readlane_b32 s87, v255, 27
	s_barrier
	v_readlane_b32 s2, v254, 0
	v_readlane_b32 s3, v255, 24
	s_load_dword s4, s[86:87], 0xc0
	s_load_dwordx2 s[6:7], s[86:87], 0x98
	s_load_dwordx2 s[8:9], s[86:87], 0xb0
	s_waitcnt lgkmcnt(0)
	s_cmp_ge_u32 s3, 3
	s_cbranch_scc1 .Ldj8_done
	s_add_u32 s69, s3, 1
	s_add_u32 s79, s3, 2
	s_cmp_eq_u32 s4, 0x100
	s_cbranch_scc0 .Ldj8_all
	s_cmp_lt_u32 s2, 128
	s_cbranch_scc1 .Ldj8_done
	s_sub_u32 s2, s2, 128
	s_movk_i32 s4, 128
.Ldj8_all:
	v_readfirstlane_b32 s5, v0
	s_lshr_b32 s5, s5, 6
	s_lshl_b32 s2, s2, 3
	s_add_u32 s2, s2, s5
	s_lshl_b32 s11, s4, 3
	s_add_u32 s8, s8, 0x76b32000
	s_addc_u32 s9, s9, 0
	v_mbcnt_lo_u32_b32 v41, -1, 0
	v_mbcnt_hi_u32_b32 v41, -1, v41
	v_lshrrev_b32_e32 v42, 3, v41
	v_and_b32_e32 v43, 7, v41
	v_lshlrev_b32_e32 v44, 13, v42
	v_lshl_add_u32 v44, v43, 4, v44
	v_add_u32_e32 v45, 0x10000, v44
	v_add_u32_e32 v46, 0x20000, v44
	v_add_u32_e32 v47, 0x30000, v44
	v_add_u32_e32 v48, 0x40000, v44
	v_add_u32_e32 v49, 0x50000, v44
	v_add_u32_e32 v50, 0x60000, v44
	v_add_u32_e32 v51, 0x70000, v44
	s_lshl_b32 s49, s5, 14
	v_mul_u32_u24_e32 v52, 0x84, v42
	v_lshl_add_u32 v52, v43, 4, v52
	v_add_u32_e32 v52, s49, v52
	v_mul_u32_u24_e32 v53, 0x420, v43
	v_lshl_add_u32 v53, v42, 2, v53
	v_add_u32_e32 v53, s49, v53
	v_lshlrev_b32_e32 v54, 14, v42
	v_lshl_add_u32 v54, v43, 4, v54
	v_add_u32_e32 v55, 0x20000, v54
	v_add_u32_e32 v56, 0x40000, v54
	v_add_u32_e32 v57, 0x60000, v54
.Ldj8_job:
	s_mov_b32 s10, s2
	s_cmp_ge_u32 s10, 0x2000
	s_cbranch_scc1 .Ldj8_done
	s_lshl_b32 s48, s69, 26
	s_load_dwordx2 s[6:7], s[86:87], 0x98
	s_load_dwordx2 s[8:9], s[86:87], 0xb0
	s_waitcnt lgkmcnt(0)
	s_add_u32 s6, s6, s48
	s_addc_u32 s7, s7, 0
	s_lshl_b32 s48, s69, 25
	s_add_u32 s8, s8, 0x76b32000
	s_addc_u32 s9, s9, 0
	s_add_u32 s8, s8, s48
	s_addc_u32 s9, s9, 0
	s_lshr_b32 s72, s10, 6
	s_and_b32 s73, s10, 63
	s_lshl_b32 s56, s72, 19
	s_lshl_b32 s57, s73, 7
	s_add_u32 s56, s56, s57
	s_add_u32 s50, s6, s56
	s_addc_u32 s51, s7, 0
	global_load_dwordx4 v[58:61], v44, s[50:51] nt
	global_load_dwordx4 v[62:65], v45, s[50:51] nt
	global_load_dwordx4 v[66:69], v46, s[50:51] nt
	global_load_dwordx4 v[70:73], v47, s[50:51] nt
	global_load_dwordx4 v[74:77], v48, s[50:51] nt
	global_load_dwordx4 v[78:81], v49, s[50:51] nt
	global_load_dwordx4 v[82:85], v50, s[50:51] nt
	global_load_dwordx4 v[86:89], v51, s[50:51] nt
	s_add_u32 s71, s10, s11
	s_cmp_ge_u32 s71, 0x2000
	s_cbranch_scc1 .Ldj8_first0
	s_lshr_b32 s72, s71, 6
	s_and_b32 s73, s71, 63
	s_lshl_b32 s56, s72, 19
	s_lshl_b32 s57, s73, 7
	s_add_u32 s56, s56, s57
	s_add_u32 s50, s6, s56
	s_addc_u32 s51, s7, 0
	global_load_dwordx4 v[90:93], v44, s[50:51] nt
	global_load_dwordx4 v[94:97], v45, s[50:51] nt
	global_load_dwordx4 v[98:101], v46, s[50:51] nt
	global_load_dwordx4 v[102:105], v47, s[50:51] nt
	global_load_dwordx4 v[106:109], v48, s[50:51] nt
	global_load_dwordx4 v[110:113], v49, s[50:51] nt
	global_load_dwordx4 v[114:117], v50, s[50:51] nt
	global_load_dwordx4 v[118:121], v51, s[50:51] nt
	s_waitcnt vmcnt(8)
	s_branch .Ldj8_loop

.Ldj8_loop:
	s_lshr_b32 s72, s10, 6
	s_and_b32 s73, s10, 63
	s_lshl_b32 s58, s73, 19
	s_lshl_b32 s59, s72, 7
	s_add_u32 s58, s58, s59
	ds_write_b32 v52, v58 offset:0
	ds_write_b32 v52, v59 offset:4
	ds_write_b32 v52, v60 offset:8
	ds_write_b32 v52, v61 offset:12
	ds_write_b32 v52, v62 offset:1056
	ds_write_b32 v52, v63 offset:1060
	ds_write_b32 v52, v64 offset:1064
	ds_write_b32 v52, v65 offset:1068
	ds_write_b32 v52, v66 offset:2112
	ds_write_b32 v52, v67 offset:2116
	ds_write_b32 v52, v68 offset:2120
	ds_write_b32 v52, v69 offset:2124
	ds_write_b32 v52, v70 offset:3168
	ds_write_b32 v52, v71 offset:3172
	ds_write_b32 v52, v72 offset:3176
	ds_write_b32 v52, v73 offset:3180
	ds_write_b32 v52, v74 offset:4224
	ds_write_b32 v52, v75 offset:4228
	ds_write_b32 v52, v76 offset:4232
	ds_write_b32 v52, v77 offset:4236
	ds_write_b32 v52, v78 offset:5280
	ds_write_b32 v52, v79 offset:5284
	ds_write_b32 v52, v80 offset:5288
	ds_write_b32 v52, v81 offset:5292
	ds_write_b32 v52, v82 offset:6336
	ds_write_b32 v52, v83 offset:6340
	ds_write_b32 v52, v84 offset:6344
	ds_write_b32 v52, v85 offset:6348
	ds_write_b32 v52, v86 offset:7392
	ds_write_b32 v52, v87 offset:7396
	ds_write_b32 v52, v88 offset:7400
	ds_write_b32 v52, v89 offset:7404
	s_waitcnt lgkmcnt(0)
	s_add_u32 s10, s71, s11
	s_cmp_ge_u32 s10, 0x2000
	s_cbranch_scc1 .Ldj8_nopfa
	s_lshr_b32 s72, s10, 6
	s_and_b32 s73, s10, 63
	s_lshl_b32 s56, s72, 19
	s_lshl_b32 s57, s73, 7
	s_add_u32 s56, s56, s57
	s_add_u32 s50, s6, s56
	s_addc_u32 s51, s7, 0
	global_load_dwordx4 v[58:61], v44, s[50:51] nt
	global_load_dwordx4 v[62:65], v45, s[50:51] nt
	global_load_dwordx4 v[66:69], v46, s[50:51] nt
	global_load_dwordx4 v[70:73], v47, s[50:51] nt
	global_load_dwordx4 v[74:77], v48, s[50:51] nt
	global_load_dwordx4 v[78:81], v49, s[50:51] nt
	global_load_dwordx4 v[82:85], v50, s[50:51] nt
	global_load_dwordx4 v[86:89], v51, s[50:51] nt

.Ldj8_goa:
	s_lshr_b32 s72, s71, 6
	s_and_b32 s73, s71, 63
	s_lshl_b32 s58, s73, 19
	s_lshl_b32 s59, s72, 7
	s_add_u32 s58, s58, s59
	ds_write_b32 v52, v90 offset:0
	ds_write_b32 v52, v91 offset:4
	ds_write_b32 v52, v92 offset:8
	ds_write_b32 v52, v93 offset:12
	ds_write_b32 v52, v94 offset:1056
	ds_write_b32 v52, v95 offset:1060
	ds_write_b32 v52, v96 offset:1064
	ds_write_b32 v52, v97 offset:1068
	ds_write_b32 v52, v98 offset:2112
	ds_write_b32 v52, v99 offset:2116
	ds_write_b32 v52, v100 offset:2120
	ds_write_b32 v52, v101 offset:2124
	ds_write_b32 v52, v102 offset:3168
	ds_write_b32 v52, v103 offset:3172
	ds_write_b32 v52, v104 offset:3176
	ds_write_b32 v52, v105 offset:3180
	ds_write_b32 v52, v106 offset:4224
	ds_write_b32 v52, v107 offset:4228
	ds_write_b32 v52, v108 offset:4232
	ds_write_b32 v52, v109 offset:4236
	ds_write_b32 v52, v110 offset:5280
	ds_write_b32 v52, v111 offset:5284
	ds_write_b32 v52, v112 offset:5288
	ds_write_b32 v52, v113 offset:5292
	ds_write_b32 v52, v114 offset:6336
	ds_write_b32 v52, v115 offset:6340
	ds_write_b32 v52, v116 offset:6344
	ds_write_b32 v52, v117 offset:6348
	ds_write_b32 v52, v118 offset:7392
	ds_write_b32 v52, v119 offset:7396
	ds_write_b32 v52, v120 offset:7400
	ds_write_b32 v52, v121 offset:7404
	s_waitcnt lgkmcnt(0)
	s_add_u32 s71, s10, s11
	s_cmp_ge_u32 s71, 0x2000
	s_cbranch_scc1 .Ldj8_nopfb
	s_lshr_b32 s72, s71, 6
	s_and_b32 s73, s71, 63
	s_lshl_b32 s56, s72, 19
	s_lshl_b32 s57, s73, 7
	s_add_u32 s56, s56, s57
	s_add_u32 s50, s6, s56
	s_addc_u32 s51, s7, 0
	global_load_dwordx4 v[90:93], v44, s[50:51] nt
	global_load_dwordx4 v[94:97], v45, s[50:51] nt
	global_load_dwordx4 v[98:101], v46, s[50:51] nt
	global_load_dwordx4 v[102:105], v47, s[50:51] nt
	global_load_dwordx4 v[106:109], v48, s[50:51] nt
	global_load_dwordx4 v[110:113], v49, s[50:51] nt
	global_load_dwordx4 v[114:117], v50, s[50:51] nt
	global_load_dwordx4 v[118:121], v51, s[50:51] nt

.Ldj8_jobend:
	s_add_u32 s69, s69, 1
	s_cmp_lt_u32 s69, s79
	s_cbranch_scc1 .Ldj8_job
.Ldj8_done:
	v_readlane_b32 s2, v254, 0
	v_readlane_b32 s3, v255, 24
	s_load_dword s4, s[86:87], 0xc0
	s_load_dwordx2 s[6:7], s[86:87], 0x90
	s_load_dwordx2 s[8:9], s[86:87], 0xb0
	s_load_dwordx2 s[74:75], s[86:87], 0x88
	s_waitcnt lgkmcnt(0)
	s_cmp_ge_u32 s3, 3
	s_cbranch_scc1 .Ldj7_done
	s_add_u32 s69, s3, 1
	s_add_u32 s79, s3, 2
	s_cmp_eq_u32 s4, 0x100
	s_cbranch_scc0 .Ldj7_all
	s_cmp_lt_u32 s2, 128
	s_cbranch_scc1 .Ldj7_done
	s_sub_u32 s2, s2, 128
	s_movk_i32 s4, 128
.Ldj7_all:
	v_readfirstlane_b32 s5, v0
	s_lshr_b32 s5, s5, 6
	s_lshl_b32 s2, s2, 3
	s_add_u32 s2, s2, s5
	s_lshl_b32 s11, s4, 3
	s_add_u32 s8, s8, 0x6eb32000
	s_addc_u32 s9, s9, 0
	v_mbcnt_lo_u32_b32 v41, -1, 0
	v_mbcnt_hi_u32_b32 v41, -1, v41
	v_lshrrev_b32_e32 v42, 3, v41
	v_and_b32_e32 v43, 7, v41
	v_lshlrev_b32_e32 v44, 15, v42
	v_lshl_add_u32 v44, v43, 4, v44
	v_add_u32_e32 v45, 0x40000, v44
	v_add_u32_e32 v46, 0x80000, v44
	v_add_u32_e32 v47, 0xc0000, v44
	v_add_u32_e32 v48, 0x100000, v44
	v_add_u32_e32 v49, 0x140000, v44
	v_add_u32_e32 v50, 0x180000, v44
	v_add_u32_e32 v51, 0x1c0000, v44
	s_lshl_b32 s49, s5, 14
	v_mul_u32_u24_e32 v52, 0x84, v42
	v_lshl_add_u32 v52, v43, 4, v52
	v_add_u32_e32 v52, s49, v52
	v_mul_u32_u24_e32 v53, 0x420, v43
	v_lshl_add_u32 v53, v42, 2, v53
	v_add_u32_e32 v53, s49, v53
	v_lshlrev_b32_e32 v54, 12, v42
	v_lshl_add_u32 v54, v43, 4, v54
	v_add_u32_e32 v55, 0x8000, v54
	v_add_u32_e32 v56, 0x10000, v54
	v_add_u32_e32 v57, 0x18000, v54
	v_lshlrev_b32_e32 v204, 2, v42
.Ldj7_job:
	s_mov_b32 s10, s2
	s_cmp_ge_u32 s10, 0x2000
	s_cbranch_scc1 .Ldj7_done
	s_lshl_b32 s48, s69, 26
	s_load_dwordx2 s[6:7], s[86:87], 0x90
	s_load_dwordx2 s[8:9], s[86:87], 0xb0
	s_load_dwordx2 s[74:75], s[86:87], 0x88
	s_waitcnt lgkmcnt(0)
	s_add_u32 s6, s6, s48
	s_addc_u32 s7, s7, 0
	s_lshl_b32 s48, s69, 25
	s_add_u32 s8, s8, 0x6eb32000
	s_addc_u32 s9, s9, 0
	s_add_u32 s8, s8, s48
	s_addc_u32 s9, s9, 0
	s_lshl_b32 s48, s69, 13
	s_add_u32 s74, s74, s48
	s_addc_u32 s75, s75, 0
	s_lshr_b32 s72, s10, 8
	s_and_b32 s73, s10, 255
	s_lshl_b32 s56, s72, 21
	s_lshl_b32 s57, s73, 7
	s_add_u32 s56, s56, s57
	s_add_u32 s50, s6, s56
	s_addc_u32 s51, s7, 0
	global_load_dwordx4 v[58:61], v44, s[50:51] nt
	global_load_dwordx4 v[62:65], v45, s[50:51] nt
	global_load_dwordx4 v[66:69], v46, s[50:51] nt
	global_load_dwordx4 v[70:73], v47, s[50:51] nt
	global_load_dwordx4 v[74:77], v48, s[50:51] nt
	global_load_dwordx4 v[78:81], v49, s[50:51] nt
	global_load_dwordx4 v[82:85], v50, s[50:51] nt
	global_load_dwordx4 v[86:89], v51, s[50:51] nt
	s_lshl_b32 s56, s72, 8
	s_add_u32 s50, s74, s56
	s_addc_u32 s51, s75, 0
	global_load_dword v230, v204, s[50:51] offset:0
	global_load_dword v231, v204, s[50:51] offset:32
	global_load_dword v232, v204, s[50:51] offset:64
	global_load_dword v233, v204, s[50:51] offset:96
	global_load_dword v234, v204, s[50:51] offset:128
	global_load_dword v235, v204, s[50:51] offset:160
	global_load_dword v236, v204, s[50:51] offset:192
	global_load_dword v237, v204, s[50:51] offset:224
	s_add_u32 s71, s10, s11
	s_cmp_ge_u32 s71, 0x2000
	s_cbranch_scc1 .Ldj7_first0
	s_lshr_b32 s72, s71, 8
	s_and_b32 s73, s71, 255
	s_lshl_b32 s56, s72, 21
	s_lshl_b32 s57, s73, 7
	s_add_u32 s56, s56, s57
	s_add_u32 s50, s6, s56
	s_addc_u32 s51, s7, 0
	global_load_dwordx4 v[90:93], v44, s[50:51] nt
	global_load_dwordx4 v[94:97], v45, s[50:51] nt
	global_load_dwordx4 v[98:101], v46, s[50:51] nt
	global_load_dwordx4 v[102:105], v47, s[50:51] nt
	global_load_dwordx4 v[106:109], v48, s[50:51] nt
	global_load_dwordx4 v[110:113], v49, s[50:51] nt
	global_load_dwordx4 v[114:117], v50, s[50:51] nt
	global_load_dwordx4 v[118:121], v51, s[50:51] nt
	s_lshl_b32 s56, s72, 8
	s_add_u32 s50, s74, s56
	s_addc_u32 s51, s75, 0
	global_load_dword v238, v204, s[50:51] offset:0
	global_load_dword v239, v204, s[50:51] offset:32
	global_load_dword v240, v204, s[50:51] offset:64
	global_load_dword v241, v204, s[50:51] offset:96
	global_load_dword v242, v204, s[50:51] offset:128
	global_load_dword v243, v204, s[50:51] offset:160
	global_load_dword v244, v204, s[50:51] offset:192
	global_load_dword v245, v204, s[50:51] offset:224
	s_waitcnt vmcnt(16)
	s_branch .Ldj7_loop

.Ldj7_loop:
	s_lshr_b32 s72, s10, 8
	s_and_b32 s73, s10, 255
	s_lshl_b32 s58, s73, 17
	s_lshl_b32 s59, s72, 7
	s_add_u32 s58, s58, s59
	v_mul_f32_e32 v58, v58, v230
	v_mul_f32_e32 v59, v59, v230
	v_mul_f32_e32 v60, v60, v230
	v_mul_f32_e32 v61, v61, v230
	v_mul_f32_e32 v62, v62, v231
	v_mul_f32_e32 v63, v63, v231
	v_mul_f32_e32 v64, v64, v231
	v_mul_f32_e32 v65, v65, v231
	v_mul_f32_e32 v66, v66, v232
	v_mul_f32_e32 v67, v67, v232
	v_mul_f32_e32 v68, v68, v232
	v_mul_f32_e32 v69, v69, v232
	v_mul_f32_e32 v70, v70, v233
	v_mul_f32_e32 v71, v71, v233
	v_mul_f32_e32 v72, v72, v233
	v_mul_f32_e32 v73, v73, v233
	v_mul_f32_e32 v74, v74, v234
	v_mul_f32_e32 v75, v75, v234
	v_mul_f32_e32 v76, v76, v234
	v_mul_f32_e32 v77, v77, v234
	v_mul_f32_e32 v78, v78, v235
	v_mul_f32_e32 v79, v79, v235
	v_mul_f32_e32 v80, v80, v235
	v_mul_f32_e32 v81, v81, v235
	v_mul_f32_e32 v82, v82, v236
	v_mul_f32_e32 v83, v83, v236
	v_mul_f32_e32 v84, v84, v236
	v_mul_f32_e32 v85, v85, v236
	v_mul_f32_e32 v86, v86, v237
	v_mul_f32_e32 v87, v87, v237
	v_mul_f32_e32 v88, v88, v237
	v_mul_f32_e32 v89, v89, v237
	ds_write_b32 v52, v58 offset:0
	ds_write_b32 v52, v59 offset:4
	ds_write_b32 v52, v60 offset:8
	ds_write_b32 v52, v61 offset:12
	ds_write_b32 v52, v62 offset:1056
	ds_write_b32 v52, v63 offset:1060
	ds_write_b32 v52, v64 offset:1064
	ds_write_b32 v52, v65 offset:1068
	ds_write_b32 v52, v66 offset:2112
	ds_write_b32 v52, v67 offset:2116
	ds_write_b32 v52, v68 offset:2120
	ds_write_b32 v52, v69 offset:2124
	ds_write_b32 v52, v70 offset:3168
	ds_write_b32 v52, v71 offset:3172
	ds_write_b32 v52, v72 offset:3176
	ds_write_b32 v52, v73 offset:3180
	ds_write_b32 v52, v74 offset:4224
	ds_write_b32 v52, v75 offset:4228
	ds_write_b32 v52, v76 offset:4232
	ds_write_b32 v52, v77 offset:4236
	ds_write_b32 v52, v78 offset:5280
	ds_write_b32 v52, v79 offset:5284
	ds_write_b32 v52, v80 offset:5288
	ds_write_b32 v52, v81 offset:5292
	ds_write_b32 v52, v82 offset:6336
	ds_write_b32 v52, v83 offset:6340
	ds_write_b32 v52, v84 offset:6344
	ds_write_b32 v52, v85 offset:6348
	ds_write_b32 v52, v86 offset:7392
	ds_write_b32 v52, v87 offset:7396
	ds_write_b32 v52, v88 offset:7400
	ds_write_b32 v52, v89 offset:7404
	s_waitcnt lgkmcnt(0)
	s_add_u32 s10, s71, s11
	s_cmp_ge_u32 s10, 0x2000
	s_cbranch_scc1 .Ldj7_nopfa
	s_lshr_b32 s72, s10, 8
	s_and_b32 s73, s10, 255
	s_lshl_b32 s56, s72, 21
	s_lshl_b32 s57, s73, 7
	s_add_u32 s56, s56, s57
	s_add_u32 s50, s6, s56
	s_addc_u32 s51, s7, 0
	global_load_dwordx4 v[58:61], v44, s[50:51] nt
	global_load_dwordx4 v[62:65], v45, s[50:51] nt
	global_load_dwordx4 v[66:69], v46, s[50:51] nt
	global_load_dwordx4 v[70:73], v47, s[50:51] nt
	global_load_dwordx4 v[74:77], v48, s[50:51] nt
	global_load_dwordx4 v[78:81], v49, s[50:51] nt
	global_load_dwordx4 v[82:85], v50, s[50:51] nt
	global_load_dwordx4 v[86:89], v51, s[50:51] nt
	s_lshl_b32 s56, s72, 8
	s_add_u32 s50, s74, s56
	s_addc_u32 s51, s75, 0
	global_load_dword v230, v204, s[50:51] offset:0
	global_load_dword v231, v204, s[50:51] offset:32
	global_load_dword v232, v204, s[50:51] offset:64
	global_load_dword v233, v204, s[50:51] offset:96
	global_load_dword v234, v204, s[50:51] offset:128
	global_load_dword v235, v204, s[50:51] offset:160
	global_load_dword v236, v204, s[50:51] offset:192
	global_load_dword v237, v204, s[50:51] offset:224
.Ldj7_nopfa:
	ds_read2_b32 v[122:123], v53 offset0:0 offset1:33
	ds_read2_b32 v[124:125], v53 offset0:66 offset1:99
	ds_read2_b32 v[126:127], v53 offset0:132 offset1:165
	ds_read2_b32 v[128:129], v53 offset0:198 offset1:231
	ds_read2_b32 v[130:131], v53 offset0:8 offset1:41
	ds_read2_b32 v[132:133], v53 offset0:74 offset1:107
	ds_read2_b32 v[134:135], v53 offset0:140 offset1:173
	ds_read2_b32 v[136:137], v53 offset0:206 offset1:239
	ds_read2_b32 v[138:139], v53 offset0:16 offset1:49
	ds_read2_b32 v[140:141], v53 offset0:82 offset1:115
	ds_read2_b32 v[142:143], v53 offset0:148 offset1:181
	ds_read2_b32 v[144:145], v53 offset0:214 offset1:247
	ds_read2_b32 v[146:147], v53 offset0:24 offset1:57
	ds_read2_b32 v[148:149], v53 offset0:90 offset1:123
	ds_read2_b32 v[180:181], v53 offset0:156 offset1:189
	ds_read2_b32 v[182:183], v53 offset0:222 offset1:255
	s_waitcnt lgkmcnt(0)
	v_cvt_pk_bf16_f32 v184, v122, v123
	v_cvt_pk_bf16_f32 v185, v124, v125
	v_cvt_pk_bf16_f32 v186, v126, v127
	v_cvt_pk_bf16_f32 v187, v128, v129
	v_cvt_pk_bf16_f32 v188, v130, v131
	v_cvt_pk_bf16_f32 v189, v132, v133
	v_cvt_pk_bf16_f32 v190, v134, v135
	v_cvt_pk_bf16_f32 v191, v136, v137
	v_cvt_pk_bf16_f32 v192, v138, v139
	v_cvt_pk_bf16_f32 v193, v140, v141
	v_cvt_pk_bf16_f32 v194, v142, v143
	v_cvt_pk_bf16_f32 v195, v144, v145
	v_cvt_pk_bf16_f32 v196, v146, v147
	v_cvt_pk_bf16_f32 v197, v148, v149
	v_cvt_pk_bf16_f32 v198, v180, v181
	v_cvt_pk_bf16_f32 v199, v182, v183
	v_add_u32_e32 v200, s58, v54
	v_add_u32_e32 v201, s58, v55
	v_add_u32_e32 v202, s58, v56
	v_add_u32_e32 v203, s58, v57
	global_store_dwordx4 v200, v[184:187], s[8:9]
	global_store_dwordx4 v201, v[188:191], s[8:9]
	global_store_dwordx4 v202, v[192:195], s[8:9]
	global_store_dwordx4 v203, v[196:199], s[8:9]
	s_cmp_ge_u32 s71, 0x2000
	s_cbranch_scc1 .Ldj7_jobend
	s_cmp_ge_u32 s10, 0x2000
	s_cbranch_scc1 .Ldj7_w4a
	s_waitcnt vmcnt(20)
	s_branch .Ldj7_goa

.Ldj7_goa:
	s_lshr_b32 s72, s71, 8
	s_and_b32 s73, s71, 255
	s_lshl_b32 s58, s73, 17
	s_lshl_b32 s59, s72, 7
	s_add_u32 s58, s58, s59
	v_mul_f32_e32 v90, v90, v238
	v_mul_f32_e32 v91, v91, v238
	v_mul_f32_e32 v92, v92, v238
	v_mul_f32_e32 v93, v93, v238
	v_mul_f32_e32 v94, v94, v239
	v_mul_f32_e32 v95, v95, v239
	v_mul_f32_e32 v96, v96, v239
	v_mul_f32_e32 v97, v97, v239
	v_mul_f32_e32 v98, v98, v240
	v_mul_f32_e32 v99, v99, v240
	v_mul_f32_e32 v100, v100, v240
	v_mul_f32_e32 v101, v101, v240
	v_mul_f32_e32 v102, v102, v241
	v_mul_f32_e32 v103, v103, v241
	v_mul_f32_e32 v104, v104, v241
	v_mul_f32_e32 v105, v105, v241
	v_mul_f32_e32 v106, v106, v242
	v_mul_f32_e32 v107, v107, v242
	v_mul_f32_e32 v108, v108, v242
	v_mul_f32_e32 v109, v109, v242
	v_mul_f32_e32 v110, v110, v243
	v_mul_f32_e32 v111, v111, v243
	v_mul_f32_e32 v112, v112, v243
	v_mul_f32_e32 v113, v113, v243
	v_mul_f32_e32 v114, v114, v244
	v_mul_f32_e32 v115, v115, v244
	v_mul_f32_e32 v116, v116, v244
	v_mul_f32_e32 v117, v117, v244
	v_mul_f32_e32 v118, v118, v245
	v_mul_f32_e32 v119, v119, v245
	v_mul_f32_e32 v120, v120, v245
	v_mul_f32_e32 v121, v121, v245
	ds_write_b32 v52, v90 offset:0
	ds_write_b32 v52, v91 offset:4
	ds_write_b32 v52, v92 offset:8
	ds_write_b32 v52, v93 offset:12
	ds_write_b32 v52, v94 offset:1056
	ds_write_b32 v52, v95 offset:1060
	ds_write_b32 v52, v96 offset:1064
	ds_write_b32 v52, v97 offset:1068
	ds_write_b32 v52, v98 offset:2112
	ds_write_b32 v52, v99 offset:2116
	ds_write_b32 v52, v100 offset:2120
	ds_write_b32 v52, v101 offset:2124
	ds_write_b32 v52, v102 offset:3168
	ds_write_b32 v52, v103 offset:3172
	ds_write_b32 v52, v104 offset:3176
	ds_write_b32 v52, v105 offset:3180
	ds_write_b32 v52, v106 offset:4224
	ds_write_b32 v52, v107 offset:4228
	ds_write_b32 v52, v108 offset:4232
	ds_write_b32 v52, v109 offset:4236
	ds_write_b32 v52, v110 offset:5280
	ds_write_b32 v52, v111 offset:5284
	ds_write_b32 v52, v112 offset:5288
	ds_write_b32 v52, v113 offset:5292
	ds_write_b32 v52, v114 offset:6336
	ds_write_b32 v52, v115 offset:6340
	ds_write_b32 v52, v116 offset:6344
	ds_write_b32 v52, v117 offset:6348
	ds_write_b32 v52, v118 offset:7392
	ds_write_b32 v52, v119 offset:7396
	ds_write_b32 v52, v120 offset:7400
	ds_write_b32 v52, v121 offset:7404
	s_waitcnt lgkmcnt(0)
	s_add_u32 s71, s10, s11
	s_cmp_ge_u32 s71, 0x2000
	s_cbranch_scc1 .Ldj7_nopfb
	s_lshr_b32 s72, s71, 8
	s_and_b32 s73, s71, 255
	s_lshl_b32 s56, s72, 21
	s_lshl_b32 s57, s73, 7
	s_add_u32 s56, s56, s57
	s_add_u32 s50, s6, s56
	s_addc_u32 s51, s7, 0
	global_load_dwordx4 v[90:93], v44, s[50:51] nt
	global_load_dwordx4 v[94:97], v45, s[50:51] nt
	global_load_dwordx4 v[98:101], v46, s[50:51] nt
	global_load_dwordx4 v[102:105], v47, s[50:51] nt
	global_load_dwordx4 v[106:109], v48, s[50:51] nt
	global_load_dwordx4 v[110:113], v49, s[50:51] nt
	global_load_dwordx4 v[114:117], v50, s[50:51] nt
	global_load_dwordx4 v[118:121], v51, s[50:51] nt
	s_lshl_b32 s56, s72, 8
	s_add_u32 s50, s74, s56
	s_addc_u32 s51, s75, 0
	global_load_dword v238, v204, s[50:51] offset:0
	global_load_dword v239, v204, s[50:51] offset:32
	global_load_dword v240, v204, s[50:51] offset:64
	global_load_dword v241, v204, s[50:51] offset:96
	global_load_dword v242, v204, s[50:51] offset:128
	global_load_dword v243, v204, s[50:51] offset:160
	global_load_dword v244, v204, s[50:51] offset:192
	global_load_dword v245, v204, s[50:51] offset:224
.Ldj7_nopfb:
	ds_read2_b32 v[122:123], v53 offset0:0 offset1:33
	ds_read2_b32 v[124:125], v53 offset0:66 offset1:99
	ds_read2_b32 v[126:127], v53 offset0:132 offset1:165
	ds_read2_b32 v[128:129], v53 offset0:198 offset1:231
	ds_read2_b32 v[130:131], v53 offset0:8 offset1:41
	ds_read2_b32 v[132:133], v53 offset0:74 offset1:107
	ds_read2_b32 v[134:135], v53 offset0:140 offset1:173
	ds_read2_b32 v[136:137], v53 offset0:206 offset1:239
	ds_read2_b32 v[138:139], v53 offset0:16 offset1:49
	ds_read2_b32 v[140:141], v53 offset0:82 offset1:115
	ds_read2_b32 v[142:143], v53 offset0:148 offset1:181
	ds_read2_b32 v[144:145], v53 offset0:214 offset1:247
	ds_read2_b32 v[146:147], v53 offset0:24 offset1:57
	ds_read2_b32 v[148:149], v53 offset0:90 offset1:123
	ds_read2_b32 v[180:181], v53 offset0:156 offset1:189
	ds_read2_b32 v[182:183], v53 offset0:222 offset1:255
	s_waitcnt lgkmcnt(0)
	v_cvt_pk_bf16_f32 v184, v122, v123
	v_cvt_pk_bf16_f32 v185, v124, v125
	v_cvt_pk_bf16_f32 v186, v126, v127
	v_cvt_pk_bf16_f32 v187, v128, v129
	v_cvt_pk_bf16_f32 v188, v130, v131
	v_cvt_pk_bf16_f32 v189, v132, v133
	v_cvt_pk_bf16_f32 v190, v134, v135
	v_cvt_pk_bf16_f32 v191, v136, v137
	v_cvt_pk_bf16_f32 v192, v138, v139
	v_cvt_pk_bf16_f32 v193, v140, v141
	v_cvt_pk_bf16_f32 v194, v142, v143
	v_cvt_pk_bf16_f32 v195, v144, v145
	v_cvt_pk_bf16_f32 v196, v146, v147
	v_cvt_pk_bf16_f32 v197, v148, v149
	v_cvt_pk_bf16_f32 v198, v180, v181
	v_cvt_pk_bf16_f32 v199, v182, v183
	v_add_u32_e32 v200, s58, v54
	v_add_u32_e32 v201, s58, v55
	v_add_u32_e32 v202, s58, v56
	v_add_u32_e32 v203, s58, v57
	global_store_dwordx4 v200, v[184:187], s[8:9]
	global_store_dwordx4 v201, v[188:191], s[8:9]
	global_store_dwordx4 v202, v[192:195], s[8:9]
	global_store_dwordx4 v203, v[196:199], s[8:9]
	s_cmp_ge_u32 s10, 0x2000
	s_cbranch_scc1 .Ldj7_jobend
	s_cmp_ge_u32 s71, 0x2000
	s_cbranch_scc1 .Ldj7_w4b
	s_waitcnt vmcnt(20)
	s_branch .Ldj7_gob
